# att: next row selection list prefetched after K phase (on top of deferred queue atomic)
# speedup vs baseline: 1.0118x; 1.0011x over previous
.LBB0_1249:
	s_or_b64 exec, exec, s[8:9]
	v_readfirstlane_b32 s8, v0
	s_cmp_gt_i32 s8, 0x101ff
	s_cbranch_scc1 .LBB0_1298
	s_add_u32 s22, s10, 0x3700000
	s_addc_u32 s23, s11, 0
	s_add_u32 s24, s10, 0x4800000
	s_addc_u32 s25, s11, 0
	s_add_u32 s26, s10, 0x32e00000
	s_addc_u32 s27, s11, 0
	s_add_u32 s31, s10, 0x34e00000
	s_addc_u32 s36, s11, 0
	s_add_u32 s37, s10, 0x16a00000
	s_addc_u32 s38, s11, 0
	s_add_u32 s39, s10, 0x37a00000
	s_addc_u32 s40, s11, 0
	s_lshl_b32 s9, s19, 4
	v_mbcnt_hi_u32_b32 v0, -1, v182
	s_add_i32 s41, s9, 0
	v_lshlrev_b32_e32 v0, 2, v0
	s_mov_b32 s15, 0
	s_add_i32 s41, s41, 0x21000
	v_mov_b32_e32 v113, 0
	s_lshl_b32 s42, s18, 1
	s_mov_b32 s43, 0x1fffe00
	s_movk_i32 s44, 0xa0
	s_mov_b32 s45, 0xffffff
	s_mov_b32 s46, 0xff61b1e6
	v_and_b32_e32 v114, 0x100, v0
	s_lshl_b32 s14, s3, 1
	s_ashr_i32 s9, s8, 31
	s_lshl_b64 s[100:101], s[8:9], 10
	s_add_u32 s100, s39, s100
	s_addc_u32 s101, s40, s101
	v_and_b32_e32 v204, 63, v194
	v_lshlrev_b32_e32 v204, 4, v204
	global_load_dwordx4 v[204:207], v204, s[100:101]
	s_waitcnt vmcnt(0)
	s_branch .LBB0_1252

.LBB0_1260:
	s_lshr_b32 s9, s9, 6
	s_mulk_i32 s9, 0x1800
	s_add_i32 s47, s9, 0
	s_ashr_i32 s9, s8, 31
	s_lshl_b64 s[16:17], s[8:9], 10
	v_and_b32_e32 v117, 63, v120
	s_add_u32 s16, s39, s16
	s_addc_u32 s17, s40, s17
	v_lshlrev_b32_e32 v3, 4, v117
	v_and_b32_e32 v116, 15, v120
	s_lshl_b64 s[8:9], s[8:9], 11
	v_lshlrev_b32_e32 v4, 6, v116
	s_add_u32 s16, s37, s8
	v_add_lshl_u32 v112, v4, s3, 1
	s_addc_u32 s17, s38, s9
	v_add_u32_e32 v3, s47, v3
	v_lshl_add_u64 v[4:5], s[16:17], 0, v[112:113]
	v_and_b32_e32 v112, 48, v120
	v_mov_b32_e32 v56, 0
	v_mov_b32_e32 v0, 0
	v_mov_b32_e32 v1, 0
	v_mov_b32_e32 v2, 0
	v_cmp_gt_u32_e32 vcc, 4, v116
	v_lshl_add_u64 v[4:5], v[4:5], 0, v[112:113]
	ds_write_b128 v3, v[204:207]
	v_mov_b32_e32 v3, 0
	s_and_saveexec_b64 s[8:9], vcc
	s_cbranch_execz .LBB0_1262
	global_load_dwordx4 v[0:3], v[4:5], off

.LBB0_1264:
	s_or_b64 exec, exec, s[8:9]
	v_lshrrev_b32_e32 v122, 3, v117
	v_lshl_add_u32 v119, v122, 2, s47
	s_waitcnt lgkmcnt(0)
	ds_read2_b32 v[4:5], v119 offset1:8
	ds_read2_b32 v[12:13], v119 offset0:16 offset1:24
	v_lshlrev_b32_e32 v6, 4, v120
	s_add_u32 s8, s20, s42
	v_and_b32_e32 v118, 0x70, v6
	s_waitcnt lgkmcnt(1)
	v_lshlrev_b32_e32 v4, 9, v4
	v_lshlrev_b32_e32 v5, 9, v5
	s_waitcnt lgkmcnt(0)
	v_lshlrev_b32_e32 v12, 9, v12
	v_lshlrev_b32_e32 v13, 9, v13
	s_addc_u32 s9, s21, 0
	v_and_or_b32 v4, v4, s43, v118
	v_and_or_b32 v8, v5, s43, v118
	v_and_or_b32 v12, v12, s43, v118
	v_and_or_b32 v16, v13, s43, v118
	global_load_dwordx4 v[4:7], v4, s[8:9]
	s_nop 0
	global_load_dwordx4 v[8:11], v8, s[8:9]
	ds_read2_b32 v[20:21], v119 offset0:32 offset1:40
	global_load_dwordx4 v[12:15], v12, s[8:9]
	s_nop 0
	global_load_dwordx4 v[16:19], v16, s[8:9]
	ds_read2_b32 v[28:29], v119 offset0:48 offset1:56
	s_add_u32 s18, s18, s42
	s_addc_u32 s19, s19, 0
	s_waitcnt lgkmcnt(1)
	v_lshlrev_b32_e32 v20, 9, v20
	v_lshlrev_b32_e32 v21, 9, v21
	s_waitcnt lgkmcnt(0)
	v_lshlrev_b32_e32 v28, 9, v28
	v_lshlrev_b32_e32 v29, 9, v29
	v_and_or_b32 v20, v20, s43, v118
	v_and_or_b32 v24, v21, s43, v118
	v_and_or_b32 v28, v28, s43, v118
	v_and_or_b32 v32, v29, s43, v118
	global_load_dwordx4 v[20:23], v20, s[8:9]
	s_nop 0
	global_load_dwordx4 v[24:27], v24, s[8:9]
	ds_read2_b32 v[36:37], v119 offset0:64 offset1:72
	global_load_dwordx4 v[28:31], v28, s[8:9]
	s_nop 0
	global_load_dwordx4 v[32:35], v32, s[8:9]
	ds_read2_b32 v[44:45], v119 offset0:80 offset1:88
	s_waitcnt lgkmcnt(1)
	v_lshlrev_b32_e32 v36, 9, v36
	v_lshlrev_b32_e32 v37, 9, v37
	s_waitcnt lgkmcnt(0)
	v_lshlrev_b32_e32 v44, 9, v44
	v_lshlrev_b32_e32 v45, 9, v45
	v_and_or_b32 v36, v36, s43, v118
	v_and_or_b32 v40, v37, s43, v118
	v_and_or_b32 v44, v44, s43, v118
	v_and_or_b32 v48, v45, s43, v118
	global_load_dwordx4 v[36:39], v36, s[8:9]
	s_nop 0
	global_load_dwordx4 v[40:43], v40, s[8:9]
	s_nop 0
	global_load_dwordx4 v[44:47], v44, s[8:9]
	s_nop 0
	global_load_dwordx4 v[48:51], v48, s[8:9]
	ds_read2_b32 v[52:53], v119 offset0:96 offset1:104
	ds_read2_b32 v[64:65], v119 offset0:112 offset1:120
	v_add_u32_e32 v112, s47, v112
	v_add_u32_e32 v121, s47, v118
	v_mad_u32_u24 v123, v116, s44, v112
	s_waitcnt lgkmcnt(1)
	v_lshlrev_b32_e32 v52, 9, v52
	v_lshlrev_b32_e32 v53, 9, v53
	s_waitcnt lgkmcnt(0)
	v_lshlrev_b32_e32 v64, 9, v64
	v_lshlrev_b32_e32 v65, 9, v65
	v_and_or_b32 v52, v52, s43, v118
	v_and_or_b32 v60, v53, s43, v118
	v_and_or_b32 v64, v64, s43, v118
	v_and_or_b32 v68, v65, s43, v118
	global_load_dwordx4 v[52:55], v52, s[8:9]
	s_nop 0
	global_load_dwordx4 v[60:63], v60, s[8:9]
	s_nop 0
	global_load_dwordx4 v[64:67], v64, s[8:9]
	s_nop 0
	global_load_dwordx4 v[68:71], v68, s[8:9]
	s_and_saveexec_b64 s[98:99], s[6:7]
	v_mov_b32_e32 v200, 1
	global_atomic_add v200, v113, v200, s[12:13] sc0
	s_or_b64 exec, exec, s[98:99]
	v_mad_u32_u24 v132, v122, s44, v121
	s_waitcnt vmcnt(15)
	ds_write_b128 v132, v[4:7] offset:1024
	s_waitcnt vmcnt(14)
	ds_write_b128 v132, v[8:11] offset:2304
	s_waitcnt vmcnt(13)
	ds_write_b128 v132, v[12:15] offset:3584
	s_waitcnt vmcnt(12)
	ds_write_b128 v132, v[16:19] offset:4864
	ds_read_b128 v[4:7], v123 offset:1024
	ds_read_b128 v[8:11], v123 offset:1088
	ds_read_b128 v[12:15], v123 offset:3584
	ds_read_b128 v[16:19], v123 offset:3648
	ds_read2_b32 v[72:73], v119 offset0:128 offset1:136
	ds_read2_b32 v[74:75], v119 offset0:144 offset1:152
	s_waitcnt lgkmcnt(5)
	v_mfma_f32_16x16x32_bf16 v[4:7], v[4:7], v[0:3], 0
	s_waitcnt lgkmcnt(1)
	v_lshlrev_b32_e32 v72, 9, v72
	v_mfma_f32_16x16x32_bf16 v[108:111], v[8:11], v[56:59], v[4:7]
	v_mfma_f32_16x16x32_bf16 v[12:15], v[12:15], v[0:3], 0
	s_nop 3
	v_and_or_b32 v4, v72, s43, v118
	v_lshlrev_b32_e32 v5, 9, v73
	s_waitcnt lgkmcnt(0)
	v_lshlrev_b32_e32 v72, 9, v74
	v_lshlrev_b32_e32 v73, 9, v75
	v_and_or_b32 v8, v5, s43, v118
	v_and_or_b32 v72, v72, s43, v118
	v_and_or_b32 v76, v73, s43, v118
	global_load_dwordx4 v[4:7], v4, s[8:9]
	s_nop 0
	global_load_dwordx4 v[8:11], v8, s[8:9]
	s_nop 0
	global_load_dwordx4 v[72:75], v72, s[8:9]
	s_nop 0
	global_load_dwordx4 v[76:79], v76, s[8:9]
	v_mfma_f32_16x16x32_bf16 v[104:107], v[16:19], v[56:59], v[12:15]
	s_waitcnt vmcnt(15)
	ds_write_b128 v132, v[20:23] offset:1024
	s_waitcnt vmcnt(14)
	ds_write_b128 v132, v[24:27] offset:2304
	s_waitcnt vmcnt(13)
	ds_write_b128 v132, v[28:31] offset:3584
	s_waitcnt vmcnt(12)
	ds_write_b128 v132, v[32:35] offset:4864
	ds_read_b128 v[12:15], v123 offset:1024
	ds_read_b128 v[16:19], v123 offset:1088
	ds_read_b128 v[20:23], v123 offset:3584
	ds_read_b128 v[24:27], v123 offset:3648
	ds_read2_b32 v[28:29], v119 offset0:160 offset1:168
	ds_read2_b32 v[30:31], v119 offset0:176 offset1:184
	s_waitcnt lgkmcnt(5)
	v_mfma_f32_16x16x32_bf16 v[12:15], v[12:15], v[0:3], 0
	s_waitcnt lgkmcnt(1)
	v_lshlrev_b32_e32 v28, 9, v28
	v_mfma_f32_16x16x32_bf16 v[100:103], v[16:19], v[56:59], v[12:15]
	v_mfma_f32_16x16x32_bf16 v[20:23], v[20:23], v[0:3], 0
	s_nop 3
	v_and_or_b32 v12, v28, s43, v118
	v_lshlrev_b32_e32 v13, 9, v29
	s_waitcnt lgkmcnt(0)
	v_lshlrev_b32_e32 v28, 9, v30
	v_lshlrev_b32_e32 v29, 9, v31
	v_and_or_b32 v16, v13, s43, v118
	v_and_or_b32 v28, v28, s43, v118
	v_and_or_b32 v32, v29, s43, v118
	global_load_dwordx4 v[12:15], v12, s[8:9]
	s_nop 0
	global_load_dwordx4 v[16:19], v16, s[8:9]
	s_nop 0
	global_load_dwordx4 v[28:31], v28, s[8:9]
	s_nop 0
	global_load_dwordx4 v[32:35], v32, s[8:9]
	v_mfma_f32_16x16x32_bf16 v[96:99], v[24:27], v[56:59], v[20:23]
	s_waitcnt vmcnt(15)
	ds_write_b128 v132, v[36:39] offset:1024
	s_waitcnt vmcnt(14)
	ds_write_b128 v132, v[40:43] offset:2304
	s_waitcnt vmcnt(13)
	ds_write_b128 v132, v[44:47] offset:3584
	s_waitcnt vmcnt(12)
	ds_write_b128 v132, v[48:51] offset:4864
	ds_read_b128 v[20:23], v123 offset:1024
	ds_read_b128 v[24:27], v123 offset:1088
	ds_read_b128 v[36:39], v123 offset:3584
	ds_read_b128 v[40:43], v123 offset:3648
	ds_read2_b32 v[44:45], v119 offset0:192 offset1:200
	ds_read2_b32 v[46:47], v119 offset0:208 offset1:216
	s_waitcnt lgkmcnt(5)
	v_mfma_f32_16x16x32_bf16 v[20:23], v[20:23], v[0:3], 0
	s_waitcnt lgkmcnt(1)
	v_lshlrev_b32_e32 v44, 9, v44
	v_mfma_f32_16x16x32_bf16 v[92:95], v[24:27], v[56:59], v[20:23]
	v_mfma_f32_16x16x32_bf16 v[36:39], v[36:39], v[0:3], 0
	s_nop 3
	v_and_or_b32 v20, v44, s43, v118
	v_lshlrev_b32_e32 v21, 9, v45
	s_waitcnt lgkmcnt(0)
	v_lshlrev_b32_e32 v44, 9, v46
	v_lshlrev_b32_e32 v45, 9, v47
	v_and_or_b32 v24, v21, s43, v118
	v_and_or_b32 v44, v44, s43, v118
	v_and_or_b32 v48, v45, s43, v118
	global_load_dwordx4 v[20:23], v20, s[8:9]
	s_nop 0
	global_load_dwordx4 v[24:27], v24, s[8:9]
	s_nop 0
	global_load_dwordx4 v[44:47], v44, s[8:9]
	s_nop 0
	global_load_dwordx4 v[48:51], v48, s[8:9]
	v_mfma_f32_16x16x32_bf16 v[88:91], v[40:43], v[56:59], v[36:39]
	s_waitcnt vmcnt(15)
	ds_write_b128 v132, v[52:55] offset:1024
	s_waitcnt vmcnt(14)
	ds_write_b128 v132, v[60:63] offset:2304
	s_waitcnt vmcnt(13)
	ds_write_b128 v132, v[64:67] offset:3584
	s_waitcnt vmcnt(12)
	ds_write_b128 v132, v[68:71] offset:4864
	ds_read_b128 v[36:39], v123 offset:1024
	ds_read_b128 v[40:43], v123 offset:1088
	ds_read_b128 v[52:55], v123 offset:3584
	ds_read_b128 v[60:63], v123 offset:3648
	ds_read2_b32 v[64:65], v119 offset0:224 offset1:232
	ds_read2_b32 v[66:67], v119 offset0:240 offset1:248
	s_waitcnt lgkmcnt(5)
	v_mfma_f32_16x16x32_bf16 v[36:39], v[36:39], v[0:3], 0
	s_waitcnt lgkmcnt(1)
	v_lshlrev_b32_e32 v64, 9, v64
	v_mfma_f32_16x16x32_bf16 v[84:87], v[40:43], v[56:59], v[36:39]
	v_mfma_f32_16x16x32_bf16 v[52:55], v[52:55], v[0:3], 0
	s_nop 3
	v_and_or_b32 v36, v64, s43, v118
	v_lshlrev_b32_e32 v37, 9, v65
	s_waitcnt lgkmcnt(0)
	v_lshlrev_b32_e32 v64, 9, v66
	v_and_or_b32 v40, v37, s43, v118
	v_and_or_b32 v64, v64, s43, v118
	v_lshlrev_b32_e32 v65, 9, v67
	global_load_dwordx4 v[36:39], v36, s[8:9]
	s_nop 0
	global_load_dwordx4 v[40:43], v40, s[8:9]
	v_and_or_b32 v65, v65, s43, v118
	global_load_dwordx4 v[124:127], v64, s[8:9]
	global_load_dwordx4 v[128:131], v65, s[8:9]
	v_mfma_f32_16x16x32_bf16 v[80:83], v[60:63], v[56:59], v[52:55]
	s_waitcnt vmcnt(15)
	ds_write_b128 v132, v[4:7] offset:1024
	s_waitcnt vmcnt(14)
	ds_write_b128 v132, v[8:11] offset:2304
	s_waitcnt vmcnt(13)
	ds_write_b128 v132, v[72:75] offset:3584
	s_waitcnt vmcnt(12)
	ds_write_b128 v132, v[76:79] offset:4864
	ds_read_b128 v[4:7], v123 offset:1024
	ds_read_b128 v[8:11], v123 offset:1088
	ds_read_b128 v[52:55], v123 offset:3584
	ds_read_b128 v[60:63], v123 offset:3648
	s_waitcnt lgkmcnt(3)
	v_mfma_f32_16x16x32_bf16 v[4:7], v[4:7], v[0:3], 0
	s_waitcnt lgkmcnt(1)
	v_mfma_f32_16x16x32_bf16 v[52:55], v[52:55], v[0:3], 0
	v_mfma_f32_16x16x32_bf16 v[76:79], v[8:11], v[56:59], v[4:7]
	s_waitcnt lgkmcnt(0)
	v_mfma_f32_16x16x32_bf16 v[72:75], v[60:63], v[56:59], v[52:55]
	s_waitcnt vmcnt(11)
	ds_write_b128 v132, v[12:15] offset:1024
	s_waitcnt vmcnt(10)
	ds_write_b128 v132, v[16:19] offset:2304
	s_waitcnt vmcnt(9)
	ds_write_b128 v132, v[28:31] offset:3584
	s_waitcnt vmcnt(8)
	ds_write_b128 v132, v[32:35] offset:4864
	ds_read_b128 v[4:7], v123 offset:1024
	ds_read_b128 v[8:11], v123 offset:1088
	ds_read_b128 v[12:15], v123 offset:3584
	ds_read_b128 v[16:19], v123 offset:3648
	s_waitcnt lgkmcnt(3)
	v_mfma_f32_16x16x32_bf16 v[4:7], v[4:7], v[0:3], 0
	s_waitcnt lgkmcnt(1)
	v_mfma_f32_16x16x32_bf16 v[12:15], v[12:15], v[0:3], 0
	v_mfma_f32_16x16x32_bf16 v[68:71], v[8:11], v[56:59], v[4:7]
	s_waitcnt lgkmcnt(0)
	v_mfma_f32_16x16x32_bf16 v[64:67], v[16:19], v[56:59], v[12:15]
	s_waitcnt vmcnt(7)
	ds_write_b128 v132, v[20:23] offset:1024
	s_waitcnt vmcnt(6)
	ds_write_b128 v132, v[24:27] offset:2304
	s_waitcnt vmcnt(5)
	ds_write_b128 v132, v[44:47] offset:3584
	s_waitcnt vmcnt(4)
	ds_write_b128 v132, v[48:51] offset:4864
	ds_read_b128 v[4:7], v123 offset:1024
	ds_read_b128 v[8:11], v123 offset:1088
	ds_read_b128 v[12:15], v123 offset:3584
	ds_read_b128 v[16:19], v123 offset:3648
	s_waitcnt lgkmcnt(3)
	v_mfma_f32_16x16x32_bf16 v[4:7], v[4:7], v[0:3], 0
	s_waitcnt lgkmcnt(1)
	v_mfma_f32_16x16x32_bf16 v[12:15], v[12:15], v[0:3], 0
	v_mfma_f32_16x16x32_bf16 v[60:63], v[8:11], v[56:59], v[4:7]
	s_waitcnt lgkmcnt(0)
	v_mfma_f32_16x16x32_bf16 v[52:55], v[16:19], v[56:59], v[12:15]
	s_waitcnt vmcnt(3)
	ds_write_b128 v132, v[36:39] offset:1024
	s_waitcnt vmcnt(2)
	ds_write_b128 v132, v[40:43] offset:2304
	s_waitcnt vmcnt(1)
	ds_write_b128 v132, v[124:127] offset:3584
	s_waitcnt vmcnt(0)
	ds_write_b128 v132, v[128:131] offset:4864
	v_readfirstlane_b32 s100, v200
	s_ashr_i32 s101, s100, 31
	s_lshl_b64 s[100:101], s[100:101], 10
	s_add_u32 s100, s39, s100
	s_addc_u32 s101, s40, s101
	v_lshlrev_b32_e32 v204, 4, v117
	global_load_dwordx4 v[204:207], v204, s[100:101]
	ds_read_b128 v[4:7], v123 offset:1024
	ds_read_b128 v[8:11], v123 offset:1088
	ds_read_b128 v[12:15], v123 offset:3584
	ds_read_b128 v[124:127], v123 offset:3648
	s_waitcnt lgkmcnt(3)
	v_mfma_f32_16x16x32_bf16 v[4:7], v[4:7], v[0:3], 0
	s_waitcnt lgkmcnt(1)
	v_mfma_f32_16x16x32_bf16 v[128:131], v[12:15], v[0:3], 0
	ds_read2_b32 v[0:1], v119 offset1:8
	ds_read2_b32 v[2:3], v119 offset0:16 offset1:24
	s_waitcnt lgkmcnt(1)
	v_lshlrev_b32_e32 v0, 9, v0
	v_and_or_b32 v0, v0, s43, v118
	v_lshlrev_b32_e32 v1, 9, v1
	v_and_or_b32 v1, v1, s43, v118
	global_load_dwordx4 v[32:35], v0, s[18:19]
	global_load_dwordx4 v[36:39], v1, s[18:19]
	s_waitcnt lgkmcnt(0)
	v_lshlrev_b32_e32 v0, 9, v2
	v_and_or_b32 v2, v0, s43, v118
	ds_read2_b32 v[0:1], v119 offset0:32 offset1:40
	v_lshlrev_b32_e32 v3, 9, v3
	v_and_or_b32 v3, v3, s43, v118
	global_load_dwordx4 v[40:43], v2, s[18:19]
	global_load_dwordx4 v[44:47], v3, s[18:19]
	ds_read2_b32 v[2:3], v119 offset0:48 offset1:56
	s_waitcnt lgkmcnt(1)
	v_lshlrev_b32_e32 v0, 9, v0
	v_and_or_b32 v0, v0, s43, v118
	v_lshlrev_b32_e32 v1, 9, v1
	v_and_or_b32 v1, v1, s43, v118
	global_load_dwordx4 v[16:19], v0, s[18:19]
	global_load_dwordx4 v[20:23], v1, s[18:19]
	s_waitcnt lgkmcnt(0)
	v_lshlrev_b32_e32 v0, 9, v2
	v_and_or_b32 v2, v0, s43, v118
	v_lshlrev_b32_e32 v3, 9, v3
	v_mfma_f32_16x16x32_bf16 v[48:51], v[8:11], v[56:59], v[4:7]
	ds_read2_b32 v[0:1], v119 offset0:64 offset1:72
	v_and_or_b32 v3, v3, s43, v118
	global_load_dwordx4 v[24:27], v2, s[18:19]
	global_load_dwordx4 v[28:31], v3, s[18:19]
	ds_read2_b32 v[8:9], v119 offset0:80 offset1:88
	v_mfma_f32_16x16x32_bf16 v[56:59], v[124:127], v[56:59], v[128:131]
	s_waitcnt lgkmcnt(1)
	v_lshlrev_b32_e32 v0, 9, v0
	v_lshlrev_b32_e32 v1, 9, v1
	v_and_or_b32 v0, v0, s43, v118
	s_waitcnt lgkmcnt(0)
	v_lshlrev_b32_e32 v8, 9, v8
	v_lshlrev_b32_e32 v9, 9, v9
	v_and_or_b32 v4, v1, s43, v118
	v_and_or_b32 v8, v8, s43, v118
	v_and_or_b32 v12, v9, s43, v118
	global_load_dwordx4 v[0:3], v0, s[18:19]
	s_nop 0
	global_load_dwordx4 v[4:7], v4, s[18:19]
	s_nop 0
	global_load_dwordx4 v[8:11], v8, s[18:19]
	s_nop 0
	global_load_dwordx4 v[12:15], v12, s[18:19]
	v_and_b32_e32 v123, 12, v116
	v_add_u32_e32 v123, v112, v123
	v_and_b32_e32 v112, 3, v120
	v_lshl_add_u32 v112, v112, 2, s41
	ds_read_b32 v136, v123
	ds_read_b32 v137, v123 offset:64
	ds_read_b32 v138, v123 offset:128
	ds_read_b32 v139, v123 offset:192
	ds_read_b32 v140, v123 offset:256
	ds_read_b32 v141, v123 offset:320
	ds_read_b32 v142, v123 offset:384
	ds_read_b32 v143, v123 offset:448
	ds_read_b32 v144, v123 offset:512
	ds_read_b32 v145, v123 offset:576
	ds_read_b32 v146, v123 offset:640
	ds_read_b32 v147, v123 offset:704
	ds_read_b32 v148, v123 offset:768
	ds_read_b32 v149, v123 offset:832
	ds_read_b32 v150, v123 offset:896
	ds_read_b32 v151, v123 offset:960
	s_movk_i32 s8, 0x7c0
	v_mov_b32_e32 v168, 0xf149f2ca
	v_mov_b32_dpp v108, v109 row_shr:4 row_mask:0xf bank_mask:0x2
	v_mov_b32_dpp v104, v105 row_shr:4 row_mask:0xf bank_mask:0x2
	v_mov_b32_dpp v100, v101 row_shr:4 row_mask:0xf bank_mask:0x2
	v_mov_b32_dpp v96, v97 row_shr:4 row_mask:0xf bank_mask:0x2
	v_mov_b32_dpp v92, v93 row_shr:4 row_mask:0xf bank_mask:0x2
	v_mov_b32_dpp v88, v89 row_shr:4 row_mask:0xf bank_mask:0x2
	v_mov_b32_dpp v84, v85 row_shr:4 row_mask:0xf bank_mask:0x2
	v_mov_b32_dpp v80, v81 row_shr:4 row_mask:0xf bank_mask:0x2
	v_mov_b32_dpp v76, v77 row_shr:4 row_mask:0xf bank_mask:0x2
	v_mov_b32_dpp v72, v73 row_shr:4 row_mask:0xf bank_mask:0x2
	v_mov_b32_dpp v68, v69 row_shr:4 row_mask:0xf bank_mask:0x2
	v_mov_b32_dpp v64, v65 row_shr:4 row_mask:0xf bank_mask:0x2
	v_mov_b32_dpp v60, v61 row_shr:4 row_mask:0xf bank_mask:0x2
	v_mov_b32_dpp v52, v53 row_shr:4 row_mask:0xf bank_mask:0x2
	v_mov_b32_dpp v48, v49 row_shr:4 row_mask:0xf bank_mask:0x2
	v_mov_b32_dpp v56, v57 row_shr:4 row_mask:0xf bank_mask:0x2
	v_mov_b32_dpp v108, v110 row_shr:8 row_mask:0xf bank_mask:0x4
	v_mov_b32_dpp v104, v106 row_shr:8 row_mask:0xf bank_mask:0x4
	v_mov_b32_dpp v100, v102 row_shr:8 row_mask:0xf bank_mask:0x4
	v_mov_b32_dpp v96, v98 row_shr:8 row_mask:0xf bank_mask:0x4
	v_mov_b32_dpp v92, v94 row_shr:8 row_mask:0xf bank_mask:0x4
	v_mov_b32_dpp v88, v90 row_shr:8 row_mask:0xf bank_mask:0x4
	v_mov_b32_dpp v84, v86 row_shr:8 row_mask:0xf bank_mask:0x4
	v_mov_b32_dpp v80, v82 row_shr:8 row_mask:0xf bank_mask:0x4
	v_mov_b32_dpp v76, v78 row_shr:8 row_mask:0xf bank_mask:0x4
	v_mov_b32_dpp v72, v74 row_shr:8 row_mask:0xf bank_mask:0x4
	v_mov_b32_dpp v68, v70 row_shr:8 row_mask:0xf bank_mask:0x4
	v_mov_b32_dpp v64, v66 row_shr:8 row_mask:0xf bank_mask:0x4
	v_mov_b32_dpp v60, v62 row_shr:8 row_mask:0xf bank_mask:0x4
	v_mov_b32_dpp v52, v54 row_shr:8 row_mask:0xf bank_mask:0x4
	v_mov_b32_dpp v48, v50 row_shr:8 row_mask:0xf bank_mask:0x4
	v_mov_b32_dpp v56, v58 row_shr:8 row_mask:0xf bank_mask:0x4
	v_mov_b32_dpp v108, v111 row_shr:12 row_mask:0xf bank_mask:0x8
	v_mov_b32_dpp v104, v107 row_shr:12 row_mask:0xf bank_mask:0x8
	v_mov_b32_dpp v100, v103 row_shr:12 row_mask:0xf bank_mask:0x8
	v_mov_b32_dpp v96, v99 row_shr:12 row_mask:0xf bank_mask:0x8
	v_mov_b32_dpp v92, v95 row_shr:12 row_mask:0xf bank_mask:0x8
	v_mov_b32_dpp v88, v91 row_shr:12 row_mask:0xf bank_mask:0x8
	v_mov_b32_dpp v84, v87 row_shr:12 row_mask:0xf bank_mask:0x8
	v_mov_b32_dpp v80, v83 row_shr:12 row_mask:0xf bank_mask:0x8
	v_mov_b32_dpp v76, v79 row_shr:12 row_mask:0xf bank_mask:0x8
	v_mov_b32_dpp v72, v75 row_shr:12 row_mask:0xf bank_mask:0x8
	v_mov_b32_dpp v68, v71 row_shr:12 row_mask:0xf bank_mask:0x8
	v_mov_b32_dpp v64, v67 row_shr:12 row_mask:0xf bank_mask:0x8
	v_mov_b32_dpp v60, v63 row_shr:12 row_mask:0xf bank_mask:0x8
	v_mov_b32_dpp v52, v55 row_shr:12 row_mask:0xf bank_mask:0x8
	v_mov_b32_dpp v48, v51 row_shr:12 row_mask:0xf bank_mask:0x8
	v_mov_b32_dpp v56, v59 row_shr:12 row_mask:0xf bank_mask:0x8
	s_waitcnt lgkmcnt(15)
	v_lshrrev_b32_e32 v152, 10, v136
	v_and_or_b32 v152, v152, s8, v112
	s_waitcnt lgkmcnt(14)
	v_lshrrev_b32_e32 v153, 10, v137
	v_and_or_b32 v153, v153, s8, v112
	s_waitcnt lgkmcnt(13)
	v_lshrrev_b32_e32 v154, 10, v138
	v_and_or_b32 v154, v154, s8, v112
	s_waitcnt lgkmcnt(12)
	v_lshrrev_b32_e32 v155, 10, v139
	v_and_or_b32 v155, v155, s8, v112
	s_waitcnt lgkmcnt(11)
	v_lshrrev_b32_e32 v156, 10, v140
	v_and_or_b32 v156, v156, s8, v112
	s_waitcnt lgkmcnt(10)
	v_lshrrev_b32_e32 v157, 10, v141
	v_and_or_b32 v157, v157, s8, v112
	s_waitcnt lgkmcnt(9)
	v_lshrrev_b32_e32 v158, 10, v142
	v_and_or_b32 v158, v158, s8, v112
	s_waitcnt lgkmcnt(8)
	v_lshrrev_b32_e32 v159, 10, v143
	v_and_or_b32 v159, v159, s8, v112
	s_waitcnt lgkmcnt(7)
	v_lshrrev_b32_e32 v160, 10, v144
	v_and_or_b32 v160, v160, s8, v112
	s_waitcnt lgkmcnt(6)
	v_lshrrev_b32_e32 v161, 10, v145
	v_and_or_b32 v161, v161, s8, v112
	s_waitcnt lgkmcnt(5)
	v_lshrrev_b32_e32 v162, 10, v146
	v_and_or_b32 v162, v162, s8, v112
	s_waitcnt lgkmcnt(4)
	v_lshrrev_b32_e32 v163, 10, v147
	v_and_or_b32 v163, v163, s8, v112
	s_waitcnt lgkmcnt(3)
	v_lshrrev_b32_e32 v164, 10, v148
	v_and_or_b32 v164, v164, s8, v112
	s_waitcnt lgkmcnt(2)
	v_lshrrev_b32_e32 v165, 10, v149
	v_and_or_b32 v165, v165, s8, v112
	s_waitcnt lgkmcnt(1)
	v_lshrrev_b32_e32 v166, 10, v150
	v_and_or_b32 v166, v166, s8, v112
	s_waitcnt lgkmcnt(0)
	v_lshrrev_b32_e32 v167, 10, v151
	v_and_or_b32 v167, v167, s8, v112
	ds_read_b32 v152, v152
	ds_read_b32 v153, v153
	ds_read_b32 v154, v154
	ds_read_b32 v155, v155
	ds_read_b32 v156, v156
	ds_read_b32 v157, v157
	ds_read_b32 v158, v158
	ds_read_b32 v159, v159
	ds_read_b32 v160, v160
	ds_read_b32 v161, v161
	ds_read_b32 v162, v162
	ds_read_b32 v163, v163
	ds_read_b32 v164, v164
	ds_read_b32 v165, v165
	ds_read_b32 v166, v166
	ds_read_b32 v167, v167
	s_waitcnt lgkmcnt(15)
	v_fmac_f32_e32 v152, 0x3e000000, v108
	v_cmp_lt_u32_e64 s[20:21], s45, v136
	s_waitcnt lgkmcnt(14)
	v_fmac_f32_e32 v153, 0x3e000000, v104
	v_cmp_lt_u32_e64 s[8:9], s45, v137
	v_cndmask_b32_e64 v110, v168, v152, s[20:21]
	s_waitcnt lgkmcnt(13)
	v_fmac_f32_e32 v154, 0x3e000000, v100
	v_cmp_lt_u32_e64 s[20:21], s45, v138
	v_cndmask_b32_e64 v109, v168, v153, s[8:9]
	s_waitcnt lgkmcnt(12)
	v_fmac_f32_e32 v155, 0x3e000000, v96
	v_cmp_lt_u32_e64 s[8:9], s45, v139
	v_cndmask_b32_e64 v102, v168, v154, s[20:21]
	s_waitcnt lgkmcnt(11)
	v_fmac_f32_e32 v156, 0x3e000000, v92
	v_cmp_lt_u32_e64 s[20:21], s45, v140
	v_cndmask_b32_e64 v101, v168, v155, s[8:9]
	s_waitcnt lgkmcnt(10)
	v_fmac_f32_e32 v157, 0x3e000000, v88
	v_cmp_lt_u32_e64 s[8:9], s45, v141
	v_cndmask_b32_e64 v94, v168, v156, s[20:21]
	s_waitcnt lgkmcnt(9)
	v_fmac_f32_e32 v158, 0x3e000000, v84
	v_cmp_lt_u32_e64 s[20:21], s45, v142
	v_cndmask_b32_e64 v93, v168, v157, s[8:9]
	s_waitcnt lgkmcnt(8)
	v_fmac_f32_e32 v159, 0x3e000000, v80
	v_cmp_lt_u32_e64 s[8:9], s45, v143
	v_cndmask_b32_e64 v86, v168, v158, s[20:21]
	s_waitcnt lgkmcnt(7)
	v_fmac_f32_e32 v160, 0x3e000000, v76
	v_cmp_lt_u32_e64 s[20:21], s45, v144
	v_cndmask_b32_e64 v85, v168, v159, s[8:9]
	s_waitcnt lgkmcnt(6)
	v_fmac_f32_e32 v161, 0x3e000000, v72
	v_cmp_lt_u32_e64 s[8:9], s45, v145
	v_cndmask_b32_e64 v78, v168, v160, s[20:21]
	s_waitcnt lgkmcnt(5)
	v_fmac_f32_e32 v162, 0x3e000000, v68
	v_cmp_lt_u32_e64 s[20:21], s45, v146
	v_cndmask_b32_e64 v77, v168, v161, s[8:9]
	s_waitcnt lgkmcnt(4)
	v_fmac_f32_e32 v163, 0x3e000000, v64
	v_cmp_lt_u32_e64 s[8:9], s45, v147
	v_cndmask_b32_e64 v70, v168, v162, s[20:21]
	s_waitcnt lgkmcnt(3)
	v_fmac_f32_e32 v164, 0x3e000000, v60
	v_cmp_lt_u32_e64 s[20:21], s45, v148
	v_cndmask_b32_e64 v69, v168, v163, s[8:9]
	s_waitcnt lgkmcnt(2)
	v_fmac_f32_e32 v165, 0x3e000000, v52
	v_cmp_lt_u32_e64 s[8:9], s45, v149
	v_cndmask_b32_e64 v62, v168, v164, s[20:21]
	s_waitcnt lgkmcnt(1)
	v_fmac_f32_e32 v166, 0x3e000000, v48
	v_cmp_lt_u32_e64 s[20:21], s45, v150
	v_cndmask_b32_e64 v61, v168, v165, s[8:9]
	s_waitcnt lgkmcnt(0)
	v_fmac_f32_e32 v167, 0x3e000000, v56
	v_cmp_lt_u32_e64 s[8:9], s45, v151
	v_cndmask_b32_e64 v50, v168, v166, s[20:21]
	s_nop 1
	v_cndmask_b32_e64 v49, v168, v167, s[8:9]
	v_max3_f32 v48, v110, s46, v109
	v_max3_f32 v48, v48, v102, v101
	v_max3_f32 v48, v48, v94, v93
	v_max3_f32 v48, v48, v86, v85
	v_max3_f32 v48, v48, v78, v77
	v_max3_f32 v48, v48, v70, v69
	v_max3_f32 v48, v48, v62, v61
	v_max3_f32 v48, v48, v50, v49
	v_mov_b32_e32 v51, v113
	v_mov_b32_e32 v68, v113
	v_bfe_u32 v98, v120, 4, 2
	v_mov_b32_dpp v51, v48 row_ror:4 row_mask:0xf bank_mask:0xf
	v_max_f32_e32 v51, v51, v51
	v_max_f32_e32 v48, v48, v51
	v_mov_b32_e32 v51, v113
	v_lshrrev_b32_e32 v100, 2, v116
	v_lshl_or_b32 v98, v98, 2, v100
	v_mov_b32_dpp v51, v48 row_ror:8 row_mask:0xf bank_mask:0xf
	v_max_f32_e32 v51, v51, v51
	v_max_f32_e32 v48, v48, v51
	v_mov_b32_e32 v51, v48
	s_nop 1
	v_permlane16_swap_b32_e32 v48, v51
	v_max_f32_e32 v51, v51, v51
	v_max_f32_e32 v48, v48, v48
	v_max_f32_e32 v48, v48, v51
	v_mov_b32_e32 v51, v48
	s_nop 1
	v_permlane32_swap_b32_e32 v48, v51
	v_max_f32_e32 v51, v51, v51
	v_max_f32_e32 v48, v48, v48
	v_max_f32_e32 v48, v48, v51
	v_sub_f32_e32 v51, v110, v48
	v_mul_f32_e32 v51, 0x3fb8aa3b, v51
	v_sub_f32_e32 v52, v109, v48
	v_exp_f32_e32 v51, v51
	v_mul_f32_e32 v52, 0x3fb8aa3b, v52
	v_sub_f32_e32 v53, v102, v48
	v_exp_f32_e32 v52, v52
	v_mul_f32_e32 v53, 0x3fb8aa3b, v53
	v_sub_f32_e32 v54, v101, v48
	v_exp_f32_e32 v53, v53
	v_mul_f32_e32 v54, 0x3fb8aa3b, v54
	v_sub_f32_e32 v56, v94, v48
	v_exp_f32_e32 v54, v54
	v_mul_f32_e32 v56, 0x3fb8aa3b, v56
	v_sub_f32_e32 v57, v93, v48
	v_add_f32_e32 v55, 0, v51
	v_exp_f32_e32 v56, v56
	v_mul_f32_e32 v57, 0x3fb8aa3b, v57
	v_sub_f32_e32 v58, v86, v48
	v_add_f32_e32 v55, v52, v55
	v_exp_f32_e32 v57, v57
	v_mul_f32_e32 v58, 0x3fb8aa3b, v58
	v_sub_f32_e32 v59, v85, v48
	v_add_f32_e32 v55, v53, v55
	v_exp_f32_e32 v58, v58
	v_mul_f32_e32 v59, 0x3fb8aa3b, v59
	v_sub_f32_e32 v60, v78, v48
	v_add_f32_e32 v55, v54, v55
	v_exp_f32_e32 v59, v59
	v_mul_f32_e32 v60, 0x3fb8aa3b, v60
	v_sub_f32_e32 v63, v77, v48
	v_sub_f32_e32 v64, v70, v48
	v_add_f32_e32 v55, v56, v55
	v_exp_f32_e32 v60, v60
	v_mul_f32_e32 v63, 0x3fb8aa3b, v63
	v_mul_f32_e32 v64, 0x3fb8aa3b, v64
	v_add_f32_e32 v55, v57, v55
	v_exp_f32_e32 v63, v63
	v_exp_f32_e32 v101, v64
	v_sub_f32_e32 v64, v69, v48
	v_add_f32_e32 v55, v58, v55
	v_mul_f32_e32 v64, 0x3fb8aa3b, v64
	v_sub_f32_e32 v62, v62, v48
	v_add_f32_e32 v55, v59, v55
	v_exp_f32_e32 v102, v64
	v_mul_f32_e32 v62, 0x3fb8aa3b, v62
	v_sub_f32_e32 v61, v61, v48
	v_add_f32_e32 v55, v60, v55
	v_exp_f32_e32 v103, v62
	v_mul_f32_e32 v61, 0x3fb8aa3b, v61
	v_sub_f32_e32 v50, v50, v48
	v_add_f32_e32 v55, v63, v55
	v_exp_f32_e32 v104, v61
	v_mul_f32_e32 v50, 0x3fb8aa3b, v50
	v_sub_f32_e32 v48, v49, v48
	v_add_f32_e32 v55, v101, v55
	v_exp_f32_e32 v105, v50
	v_mul_f32_e32 v48, 0x3fb8aa3b, v48
	v_add_f32_e32 v55, v102, v55
	v_exp_f32_e32 v106, v48
	v_add_f32_e32 v48, v103, v55
	v_add_f32_e32 v48, v104, v48
	v_add_f32_e32 v48, v105, v48
	v_add_f32_e32 v48, v106, v48
	v_mov_b32_e32 v50, v113
	v_mov_b32_e32 v55, v113
	v_add_f32_dpp v48, v48, v48 row_ror:4 row_mask:0xf bank_mask:0xf bound_ctrl:1
	v_mov_b32_e32 v61, v113
	v_mov_b32_dpp v50, v51 row_shl:8 row_mask:0xf bank_mask:0x1 bound_ctrl:1
	v_add_f32_dpp v48, v48, v48 row_ror:8 row_mask:0xf bank_mask:0xf bound_ctrl:1
	v_mov_b32_e32 v49, v48
	s_nop 1
	v_permlane16_swap_b32_e32 v48, v49
	v_add_f32_e32 v96, v48, v49
	v_mov_b32_e32 v49, v113
	v_cndmask_b32_e32 v48, 0, v51, vcc
	v_mov_b32_dpp v55, v51 row_shl:12 row_mask:0xf bank_mask:0x1 bound_ctrl:1
	v_mov_b32_dpp v49, v51 row_shl:4 row_mask:0xf bank_mask:0x1 bound_ctrl:1
	v_cndmask_b32_e32 v51, 0, v52, vcc
	v_mov_b32_dpp v61, v52 row_shl:4 row_mask:0xf bank_mask:0x1 bound_ctrl:1
	v_mov_b32_e32 v62, v113
	v_mov_b32_e32 v64, v113
	v_cvt_pk_bf16_f32 v76, v48, v49
	v_cvt_pk_bf16_f32 v77, v50, v55
	v_cvt_pk_bf16_f32 v78, v51, v61
	v_mov_b32_e32 v49, v113
	v_mov_b32_e32 v50, v113
	v_mov_b32_e32 v51, v113
	v_mov_b32_dpp v62, v52 row_shl:8 row_mask:0xf bank_mask:0x1 bound_ctrl:1
	v_mov_b32_dpp v64, v52 row_shl:12 row_mask:0xf bank_mask:0x1 bound_ctrl:1
	v_cndmask_b32_e32 v48, 0, v53, vcc
	v_mov_b32_dpp v49, v53 row_shl:4 row_mask:0xf bank_mask:0x1 bound_ctrl:1
	v_mov_b32_dpp v50, v53 row_shl:8 row_mask:0xf bank_mask:0x1 bound_ctrl:1
	v_mov_b32_dpp v51, v53 row_shl:12 row_mask:0xf bank_mask:0x1 bound_ctrl:1
	v_cvt_pk_bf16_f32 v79, v62, v64
	v_mov_b32_e32 v53, v113
	v_cvt_pk_bf16_f32 v64, v48, v49
	v_cvt_pk_bf16_f32 v65, v50, v51
	v_mov_b32_e32 v49, v113
	v_mov_b32_e32 v50, v113
	v_mov_b32_e32 v51, v113
	v_cndmask_b32_e32 v52, 0, v54, vcc
	v_mov_b32_dpp v53, v54 row_shl:4 row_mask:0xf bank_mask:0x1 bound_ctrl:1
	v_cndmask_b32_e32 v48, 0, v56, vcc
	v_mov_b32_dpp v49, v56 row_shl:4 row_mask:0xf bank_mask:0x1 bound_ctrl:1
	v_mov_b32_dpp v50, v56 row_shl:8 row_mask:0xf bank_mask:0x1 bound_ctrl:1
	v_mov_b32_dpp v51, v56 row_shl:12 row_mask:0xf bank_mask:0x1 bound_ctrl:1
	v_cvt_pk_bf16_f32 v66, v52, v53
	v_cvt_pk_bf16_f32 v52, v48, v49
	v_cvt_pk_bf16_f32 v53, v50, v51
	v_mov_b32_e32 v51, v113
	ds_read2_b32 v[48:49], v119 offset0:96 offset1:104
	v_cndmask_b32_e32 v50, 0, v58, vcc
	v_mov_b32_dpp v51, v58 row_shl:4 row_mask:0xf bank_mask:0x1 bound_ctrl:1
	v_cvt_pk_bf16_f32 v72, v50, v51
	ds_read2_b32 v[50:51], v119 offset0:112 offset1:120
	s_waitcnt lgkmcnt(1)
	v_lshlrev_b32_e32 v48, 9, v48
	v_and_or_b32 v48, v48, s43, v118
	v_lshlrev_b32_e32 v49, 9, v49
	v_and_or_b32 v49, v49, s43, v118
	global_load_dwordx4 v[80:83], v48, s[18:19]
	global_load_dwordx4 v[84:87], v49, s[18:19]
	s_waitcnt lgkmcnt(0)
	v_lshlrev_b32_e32 v48, 9, v50
	v_and_or_b32 v48, v48, s43, v118
	v_lshlrev_b32_e32 v49, 9, v51
	v_and_or_b32 v49, v49, s43, v118
	global_load_dwordx4 v[88:91], v48, s[18:19]
	global_load_dwordx4 v[92:95], v49, s[18:19]
	v_mov_b32_e32 v55, v113
	v_mov_b32_e32 v61, v113
	v_mov_b32_e32 v56, v113
	v_mov_b32_dpp v55, v54 row_shl:8 row_mask:0xf bank_mask:0x1 bound_ctrl:1
	v_mov_b32_dpp v61, v54 row_shl:12 row_mask:0xf bank_mask:0x1 bound_ctrl:1
	v_cvt_pk_bf16_f32 v67, v55, v61
	v_mov_b32_e32 v55, v113
	v_mov_b32_e32 v61, v113
	v_cndmask_b32_e32 v54, 0, v57, vcc
	v_mov_b32_dpp v55, v57 row_shl:4 row_mask:0xf bank_mask:0x1 bound_ctrl:1
	v_mov_b32_dpp v56, v57 row_shl:8 row_mask:0xf bank_mask:0x1 bound_ctrl:1
	v_mov_b32_dpp v61, v57 row_shl:12 row_mask:0xf bank_mask:0x1 bound_ctrl:1
	v_cvt_pk_bf16_f32 v54, v54, v55
	v_cvt_pk_bf16_f32 v55, v56, v61
	v_mov_b32_e32 v56, v113
	v_mov_b32_e32 v57, v113
	v_mov_b32_e32 v61, v113
	v_mov_b32_dpp v56, v58 row_shl:8 row_mask:0xf bank_mask:0x1 bound_ctrl:1
	v_mov_b32_dpp v57, v58 row_shl:12 row_mask:0xf bank_mask:0x1 bound_ctrl:1
	v_cndmask_b32_e32 v58, 0, v59, vcc
	v_mov_b32_dpp v61, v59 row_shl:4 row_mask:0xf bank_mask:0x1 bound_ctrl:1
	v_mov_b32_e32 v62, v113
	v_mov_b32_dpp v68, v59 row_shl:12 row_mask:0xf bank_mask:0x1 bound_ctrl:1
	v_cvt_pk_bf16_f32 v74, v58, v61
	v_mov_b32_dpp v62, v59 row_shl:8 row_mask:0xf bank_mask:0x1 bound_ctrl:1
	v_mov_b32_e32 v49, v113
	v_mov_b32_e32 v50, v113
	v_mov_b32_e32 v51, v113
	v_mov_b32_e32 v58, v113
	v_mov_b32_e32 v59, v113
	v_cvt_pk_bf16_f32 v73, v56, v57
	v_cndmask_b32_e32 v48, 0, v60, vcc
	v_mov_b32_dpp v49, v60 row_shl:4 row_mask:0xf bank_mask:0x1 bound_ctrl:1
	v_mov_b32_dpp v50, v60 row_shl:8 row_mask:0xf bank_mask:0x1 bound_ctrl:1
	v_mov_b32_dpp v51, v60 row_shl:12 row_mask:0xf bank_mask:0x1 bound_ctrl:1
	v_mov_b32_e32 v57, v113
	v_mov_b32_dpp v58, v63 row_shl:8 row_mask:0xf bank_mask:0x1 bound_ctrl:1
	v_mov_b32_dpp v59, v63 row_shl:12 row_mask:0xf bank_mask:0x1 bound_ctrl:1
	v_cvt_pk_bf16_f32 v75, v62, v68
	v_cndmask_b32_e32 v56, 0, v63, vcc
	v_mov_b32_dpp v57, v63 row_shl:4 row_mask:0xf bank_mask:0x1 bound_ctrl:1
	v_cvt_pk_bf16_f32 v68, v48, v49
	v_cvt_pk_bf16_f32 v69, v50, v51
	v_cvt_pk_bf16_f32 v71, v58, v59
	v_mov_b32_e32 v49, v113
	v_mov_b32_e32 v50, v113
	v_mov_b32_e32 v51, v113
	v_mov_b32_e32 v58, v113
	v_mov_b32_e32 v59, v113
	v_cvt_pk_bf16_f32 v70, v56, v57
	v_cndmask_b32_e32 v48, 0, v101, vcc
	v_mov_b32_dpp v49, v101 row_shl:4 row_mask:0xf bank_mask:0x1 bound_ctrl:1
	v_mov_b32_dpp v50, v101 row_shl:8 row_mask:0xf bank_mask:0x1 bound_ctrl:1
	v_mov_b32_dpp v51, v101 row_shl:12 row_mask:0xf bank_mask:0x1 bound_ctrl:1
	v_mov_b32_e32 v57, v113
	v_mov_b32_dpp v58, v102 row_shl:8 row_mask:0xf bank_mask:0x1 bound_ctrl:1
	v_mov_b32_dpp v59, v102 row_shl:12 row_mask:0xf bank_mask:0x1 bound_ctrl:1
	v_cndmask_b32_e32 v56, 0, v102, vcc
	v_mov_b32_dpp v57, v102 row_shl:4 row_mask:0xf bank_mask:0x1 bound_ctrl:1
	v_cvt_pk_bf16_f32 v60, v48, v49
	v_cvt_pk_bf16_f32 v61, v50, v51
	v_cvt_pk_bf16_f32 v63, v58, v59
	v_mov_b32_e32 v49, v113
	v_mov_b32_e32 v50, v113
	v_mov_b32_e32 v51, v113
	v_mov_b32_e32 v59, v113
	v_mov_b32_e32 v101, v113
	v_mov_b32_e32 v102, v113
	v_cndmask_b32_e32 v48, 0, v103, vcc
	v_mov_b32_dpp v49, v103 row_shl:4 row_mask:0xf bank_mask:0x1 bound_ctrl:1
	v_mov_b32_dpp v50, v103 row_shl:8 row_mask:0xf bank_mask:0x1 bound_ctrl:1
	v_mov_b32_dpp v51, v103 row_shl:12 row_mask:0xf bank_mask:0x1 bound_ctrl:1
	v_cndmask_b32_e32 v58, 0, v104, vcc
	v_mov_b32_dpp v59, v104 row_shl:4 row_mask:0xf bank_mask:0x1 bound_ctrl:1
	v_mov_b32_dpp v101, v104 row_shl:8 row_mask:0xf bank_mask:0x1 bound_ctrl:1
	v_mov_b32_dpp v102, v104 row_shl:12 row_mask:0xf bank_mask:0x1 bound_ctrl:1
	v_cvt_pk_bf16_f32 v62, v56, v57
	v_cvt_pk_bf16_f32 v56, v48, v49
	v_cvt_pk_bf16_f32 v57, v50, v51
	v_cvt_pk_bf16_f32 v58, v58, v59
	v_cvt_pk_bf16_f32 v59, v101, v102
	v_mov_b32_e32 v49, v113
	v_mov_b32_e32 v50, v113
	v_mov_b32_e32 v51, v113
	v_mov_b32_e32 v102, v113
	v_mov_b32_e32 v103, v113
	v_mov_b32_e32 v104, v113
	v_lshlrev_b32_e32 v100, 3, v120
	v_mov_b32_e32 v97, v96
	v_cndmask_b32_e32 v48, 0, v105, vcc
	v_mov_b32_dpp v49, v105 row_shl:4 row_mask:0xf bank_mask:0x1 bound_ctrl:1
	v_mov_b32_dpp v50, v105 row_shl:8 row_mask:0xf bank_mask:0x1 bound_ctrl:1
	v_mov_b32_dpp v51, v105 row_shl:12 row_mask:0xf bank_mask:0x1 bound_ctrl:1
	v_cndmask_b32_e32 v101, 0, v106, vcc
	v_mov_b32_dpp v102, v106 row_shl:4 row_mask:0xf bank_mask:0x1 bound_ctrl:1
	v_mov_b32_dpp v103, v106 row_shl:8 row_mask:0xf bank_mask:0x1 bound_ctrl:1
	v_mov_b32_dpp v104, v106 row_shl:12 row_mask:0xf bank_mask:0x1 bound_ctrl:1
	v_mul_u32_u24_e32 v98, 0xa0, v98
	v_and_b32_e32 v100, 24, v100
	v_mul_u32_u24_e32 v99, 0xa0, v122
	v_permlane32_swap_b32_e32 v96, v97
	v_cvt_pk_bf16_f32 v48, v48, v49
	v_cvt_pk_bf16_f32 v49, v50, v51
	v_cvt_pk_bf16_f32 v50, v101, v102
	v_cvt_pk_bf16_f32 v51, v103, v104
	v_add3_u32 v110, s47, v98, v100
	v_add_u32_e32 v111, v121, v99
	s_waitcnt vmcnt(15)
	ds_write_b128 v111, v[32:35] offset:1024
	s_waitcnt vmcnt(14)
	ds_write_b128 v111, v[36:39] offset:2304
	s_waitcnt vmcnt(13)
	ds_write_b128 v111, v[40:43] offset:3584
	s_waitcnt vmcnt(12)
	ds_write_b128 v111, v[44:47] offset:4864
	ds_read_b64_tr_b16 v[34:35], v110 offset:3584
	ds_read_b64_tr_b16 v[32:33], v110 offset:1024
	ds_read_b64_tr_b16 v[36:37], v110 offset:1056
	ds_read_b64_tr_b16 v[40:41], v110 offset:1088
	ds_read_b64_tr_b16 v[44:45], v110 offset:1120
	ds_read_b64_tr_b16 v[38:39], v110 offset:3616
	ds_read_b64_tr_b16 v[42:43], v110 offset:3648
	ds_read_b64_tr_b16 v[46:47], v110 offset:3680
	ds_read2_b32 v[98:99], v119 offset0:128 offset1:136
	ds_read2_b32 v[106:107], v119 offset0:144 offset1:152
	s_waitcnt lgkmcnt(8)
	v_mfma_f32_16x16x32_bf16 v[32:35], v[76:79], v[32:35], 0
	s_waitcnt lgkmcnt(1)
	v_lshlrev_b32_e32 v98, 9, v98
	v_and_or_b32 v108, v98, s43, v118
	v_lshlrev_b32_e32 v98, 9, v99
	s_waitcnt lgkmcnt(0)
	v_lshlrev_b32_e32 v106, 9, v106
	v_and_or_b32 v109, v98, s43, v118
	v_and_or_b32 v112, v106, s43, v118
	v_lshlrev_b32_e32 v106, 9, v107
	global_load_dwordx4 v[98:101], v108, s[18:19]
	global_load_dwordx4 v[102:105], v109, s[18:19]
	v_and_or_b32 v124, v106, s43, v118
	global_load_dwordx4 v[106:109], v112, s[18:19]
	global_load_dwordx4 v[120:123], v124, s[18:19]
	v_mfma_f32_16x16x32_bf16 v[36:39], v[76:79], v[36:39], 0
	v_mfma_f32_16x16x32_bf16 v[40:43], v[76:79], v[40:43], 0
	v_mfma_f32_16x16x32_bf16 v[44:47], v[76:79], v[44:47], 0
	s_waitcnt vmcnt(15)
	ds_write_b128 v111, v[16:19] offset:1024
	s_waitcnt vmcnt(14)
	ds_write_b128 v111, v[20:23] offset:2304
	s_waitcnt vmcnt(13)
	ds_write_b128 v111, v[24:27] offset:3584
	s_waitcnt vmcnt(12)
	ds_write_b128 v111, v[28:31] offset:4864
	ds_read_b64_tr_b16 v[18:19], v110 offset:3584
	ds_read_b64_tr_b16 v[16:17], v110 offset:1024
	ds_read_b64_tr_b16 v[20:21], v110 offset:1056
	ds_read_b64_tr_b16 v[24:25], v110 offset:1088
	ds_read_b64_tr_b16 v[28:29], v110 offset:1120
	ds_read_b64_tr_b16 v[22:23], v110 offset:3616
	ds_read_b64_tr_b16 v[26:27], v110 offset:3648
	ds_read_b64_tr_b16 v[30:31], v110 offset:3680
	s_waitcnt lgkmcnt(6)
	v_mfma_f32_16x16x32_bf16 v[16:19], v[64:67], v[16:19], v[32:35]
	s_waitcnt lgkmcnt(1)
	v_mfma_f32_16x16x32_bf16 v[24:27], v[64:67], v[24:27], v[40:43]
	s_nop 0
	ds_read2_b32 v[32:33], v119 offset0:160 offset1:168
	s_waitcnt lgkmcnt(0)
	v_lshlrev_b32_e32 v32, 9, v32
	ds_read2_b32 v[40:41], v119 offset0:176 offset1:184
	v_lshlrev_b32_e32 v33, 9, v33
	v_mfma_f32_16x16x32_bf16 v[20:23], v[64:67], v[20:23], v[36:39]
	v_and_or_b32 v32, v32, s43, v118
	s_waitcnt lgkmcnt(0)
	v_lshlrev_b32_e32 v40, 9, v40
	v_and_or_b32 v36, v33, s43, v118
	v_and_or_b32 v112, v40, s43, v118
	v_lshlrev_b32_e32 v40, 9, v41
	global_load_dwordx4 v[32:35], v32, s[18:19]
	s_nop 0
	global_load_dwordx4 v[36:39], v36, s[18:19]
	v_and_or_b32 v124, v40, s43, v118
	global_load_dwordx4 v[40:43], v112, s[18:19]
	global_load_dwordx4 v[76:79], v124, s[18:19]
	v_mfma_f32_16x16x32_bf16 v[28:31], v[64:67], v[28:31], v[44:47]
	s_waitcnt vmcnt(15)
	ds_write_b128 v111, v[0:3] offset:1024
	s_waitcnt vmcnt(14)
	ds_write_b128 v111, v[4:7] offset:2304
	s_waitcnt vmcnt(13)
	ds_write_b128 v111, v[8:11] offset:3584
	s_waitcnt vmcnt(12)
	ds_write_b128 v111, v[12:15] offset:4864
	ds_read_b64_tr_b16 v[2:3], v110 offset:3584
	ds_read_b64_tr_b16 v[0:1], v110 offset:1024
	ds_read_b64_tr_b16 v[4:5], v110 offset:1056
	ds_read_b64_tr_b16 v[8:9], v110 offset:1088
	ds_read_b64_tr_b16 v[12:13], v110 offset:1120
	ds_read_b64_tr_b16 v[6:7], v110 offset:3616
	ds_read_b64_tr_b16 v[10:11], v110 offset:3648
	ds_read_b64_tr_b16 v[14:15], v110 offset:3680
	s_waitcnt lgkmcnt(6)
	v_mfma_f32_16x16x32_bf16 v[0:3], v[52:55], v[0:3], v[16:19]
	s_waitcnt lgkmcnt(1)
	v_mfma_f32_16x16x32_bf16 v[8:11], v[52:55], v[8:11], v[24:27]
	s_nop 0
	ds_read2_b32 v[16:17], v119 offset0:192 offset1:200
	s_waitcnt lgkmcnt(0)
	v_lshlrev_b32_e32 v16, 9, v16
	ds_read2_b32 v[24:25], v119 offset0:208 offset1:216
	v_lshlrev_b32_e32 v17, 9, v17
	v_mfma_f32_16x16x32_bf16 v[4:7], v[52:55], v[4:7], v[20:23]
	v_and_or_b32 v16, v16, s43, v118
	s_waitcnt lgkmcnt(0)
	v_lshlrev_b32_e32 v24, 9, v24
	v_and_or_b32 v20, v17, s43, v118
	v_and_or_b32 v64, v24, s43, v118
	v_lshlrev_b32_e32 v24, 9, v25
	global_load_dwordx4 v[16:19], v16, s[18:19]
	s_nop 0
	global_load_dwordx4 v[20:23], v20, s[18:19]
	v_and_or_b32 v65, v24, s43, v118
	global_load_dwordx4 v[24:27], v64, s[18:19]
	global_load_dwordx4 v[44:47], v65, s[18:19]
	v_mfma_f32_16x16x32_bf16 v[12:15], v[52:55], v[12:15], v[28:31]
	s_waitcnt vmcnt(15)
	ds_write_b128 v111, v[80:83] offset:1024
	s_waitcnt vmcnt(14)
	ds_write_b128 v111, v[84:87] offset:2304
	s_waitcnt vmcnt(13)
	ds_write_b128 v111, v[88:91] offset:3584
	s_waitcnt vmcnt(12)
	ds_write_b128 v111, v[92:95] offset:4864
	ds_read_b64_tr_b16 v[30:31], v110 offset:3584
	ds_read_b64_tr_b16 v[28:29], v110 offset:1024
	ds_read_b64_tr_b16 v[52:53], v110 offset:1056
	ds_read_b64_tr_b16 v[64:65], v110 offset:1088
	ds_read_b64_tr_b16 v[80:81], v110 offset:1120
	ds_read_b64_tr_b16 v[54:55], v110 offset:3616
	ds_read_b64_tr_b16 v[66:67], v110 offset:3648
	ds_read_b64_tr_b16 v[82:83], v110 offset:3680
	s_waitcnt lgkmcnt(6)
	v_mfma_f32_16x16x32_bf16 v[0:3], v[72:75], v[28:31], v[0:3]
	ds_read2_b32 v[28:29], v119 offset0:224 offset1:232
	s_waitcnt lgkmcnt(0)
	v_lshlrev_b32_e32 v28, 9, v28
	v_mfma_f32_16x16x32_bf16 v[8:11], v[72:75], v[64:67], v[8:11]
	ds_read2_b32 v[64:65], v119 offset0:240 offset1:248
	v_and_or_b32 v66, v28, s43, v118
	v_lshlrev_b32_e32 v28, 9, v29
	v_and_or_b32 v67, v28, s43, v118
	v_mfma_f32_16x16x32_bf16 v[4:7], v[72:75], v[52:55], v[4:7]
	s_waitcnt lgkmcnt(0)
	v_lshlrev_b32_e32 v64, 9, v64
	v_and_or_b32 v88, v64, s43, v118
	v_lshlrev_b32_e32 v64, 9, v65
	global_load_dwordx4 v[28:31], v66, s[18:19]
	global_load_dwordx4 v[52:55], v67, s[18:19]
	v_and_or_b32 v89, v64, s43, v118
	global_load_dwordx4 v[64:67], v88, s[18:19]
	global_load_dwordx4 v[84:87], v89, s[18:19]
	v_mfma_f32_16x16x32_bf16 v[12:15], v[72:75], v[80:83], v[12:15]
	s_waitcnt vmcnt(15)
	ds_write_b128 v111, v[98:101] offset:1024
	s_waitcnt vmcnt(14)
	ds_write_b128 v111, v[102:105] offset:2304
	s_waitcnt vmcnt(13)
	ds_write_b128 v111, v[106:109] offset:3584
	s_waitcnt vmcnt(12)
	ds_write_b128 v111, v[120:123] offset:4864
	ds_read_b64_tr_b16 v[74:75], v110 offset:3584
	ds_read_b64_tr_b16 v[72:73], v110 offset:1024
	ds_read_b64_tr_b16 v[80:81], v110 offset:1056
	ds_read_b64_tr_b16 v[88:89], v110 offset:1088
	ds_read_b64_tr_b16 v[92:93], v110 offset:1120
	ds_read_b64_tr_b16 v[82:83], v110 offset:3616
	ds_read_b64_tr_b16 v[90:91], v110 offset:3648
	ds_read_b64_tr_b16 v[94:95], v110 offset:3680
	s_waitcnt lgkmcnt(6)
	v_mfma_f32_16x16x32_bf16 v[0:3], v[68:71], v[72:75], v[0:3]
	s_waitcnt lgkmcnt(2)
	v_mfma_f32_16x16x32_bf16 v[4:7], v[68:71], v[80:83], v[4:7]
	s_waitcnt lgkmcnt(1)
	v_mfma_f32_16x16x32_bf16 v[8:11], v[68:71], v[88:91], v[8:11]
	s_waitcnt lgkmcnt(0)
	v_mfma_f32_16x16x32_bf16 v[12:15], v[68:71], v[92:95], v[12:15]
	s_waitcnt vmcnt(11)
	ds_write_b128 v111, v[32:35] offset:1024
	s_waitcnt vmcnt(10)
	ds_write_b128 v111, v[36:39] offset:2304
	s_waitcnt vmcnt(9)
	ds_write_b128 v111, v[40:43] offset:3584
	s_waitcnt vmcnt(8)
	ds_write_b128 v111, v[76:79] offset:4864
	ds_read_b64_tr_b16 v[34:35], v110 offset:3584
	ds_read_b64_tr_b16 v[32:33], v110 offset:1024
	ds_read_b64_tr_b16 v[36:37], v110 offset:1056
	ds_read_b64_tr_b16 v[40:41], v110 offset:1088
	ds_read_b64_tr_b16 v[68:69], v110 offset:1120
	ds_read_b64_tr_b16 v[38:39], v110 offset:3616
	ds_read_b64_tr_b16 v[42:43], v110 offset:3648
	ds_read_b64_tr_b16 v[70:71], v110 offset:3680
	s_waitcnt lgkmcnt(6)
	v_mfma_f32_16x16x32_bf16 v[0:3], v[60:63], v[32:35], v[0:3]
	s_waitcnt lgkmcnt(2)
	v_mfma_f32_16x16x32_bf16 v[4:7], v[60:63], v[36:39], v[4:7]
	s_waitcnt lgkmcnt(1)
	v_mfma_f32_16x16x32_bf16 v[8:11], v[60:63], v[40:43], v[8:11]
	s_waitcnt lgkmcnt(0)
	v_mfma_f32_16x16x32_bf16 v[12:15], v[60:63], v[68:71], v[12:15]
	s_waitcnt vmcnt(7)
	ds_write_b128 v111, v[16:19] offset:1024
	s_waitcnt vmcnt(6)
	ds_write_b128 v111, v[20:23] offset:2304
	s_waitcnt vmcnt(5)
	ds_write_b128 v111, v[24:27] offset:3584
	s_waitcnt vmcnt(4)
	ds_write_b128 v111, v[44:47] offset:4864
	ds_read_b64_tr_b16 v[18:19], v110 offset:3584
	ds_read_b64_tr_b16 v[16:17], v110 offset:1024
	ds_read_b64_tr_b16 v[20:21], v110 offset:1056
	ds_read_b64_tr_b16 v[24:25], v110 offset:1088
	ds_read_b64_tr_b16 v[32:33], v110 offset:1120
	ds_read_b64_tr_b16 v[22:23], v110 offset:3616
	ds_read_b64_tr_b16 v[26:27], v110 offset:3648
	ds_read_b64_tr_b16 v[34:35], v110 offset:3680
	s_waitcnt lgkmcnt(6)
	v_mfma_f32_16x16x32_bf16 v[0:3], v[56:59], v[16:19], v[0:3]
	s_waitcnt lgkmcnt(2)
	v_mfma_f32_16x16x32_bf16 v[4:7], v[56:59], v[20:23], v[4:7]
	s_waitcnt lgkmcnt(1)
	v_mfma_f32_16x16x32_bf16 v[8:11], v[56:59], v[24:27], v[8:11]
	s_waitcnt lgkmcnt(0)
	v_mfma_f32_16x16x32_bf16 v[16:19], v[56:59], v[32:35], v[12:15]
	s_waitcnt vmcnt(3)
	ds_write_b128 v111, v[28:31] offset:1024
	s_waitcnt vmcnt(2)
	ds_write_b128 v111, v[52:55] offset:2304
	s_waitcnt vmcnt(1)
	ds_write_b128 v111, v[64:67] offset:3584
	s_waitcnt vmcnt(0)
	ds_write_b128 v111, v[84:87] offset:4864
	ds_read_b64_tr_b16 v[14:15], v110 offset:3584
	ds_read_b64_tr_b16 v[12:13], v110 offset:1024
	ds_read_b64_tr_b16 v[20:21], v110 offset:1056
	ds_read_b64_tr_b16 v[24:25], v110 offset:1088
	ds_read_b64_tr_b16 v[28:29], v110 offset:1120
	ds_read_b64_tr_b16 v[22:23], v110 offset:3616
	ds_read_b64_tr_b16 v[26:27], v110 offset:3648
	ds_read_b64_tr_b16 v[30:31], v110 offset:3680
	s_waitcnt lgkmcnt(6)
	v_mfma_f32_16x16x32_bf16 v[12:15], v[48:51], v[12:15], v[0:3]
	v_cmp_gt_u32_e32 vcc, 16, v117
	s_waitcnt lgkmcnt(1)
	v_mfma_f32_16x16x32_bf16 v[0:3], v[48:51], v[24:27], v[8:11]
	s_waitcnt lgkmcnt(0)
	v_mfma_f32_16x16x32_bf16 v[8:11], v[48:51], v[28:31], v[16:19]
	s_nop 2
	v_add_f32_e32 v19, v96, v97
	ds_bpermute_b32 v16, v114, v19
	ds_bpermute_b32 v17, v114, v19 offset:4
	ds_bpermute_b32 v18, v114, v19 offset:8
	ds_bpermute_b32 v19, v114, v19 offset:12
	v_mfma_f32_16x16x32_bf16 v[4:7], v[48:51], v[20:23], v[4:7]
	s_and_saveexec_b64 s[8:9], vcc
	s_cbranch_execz .LBB0_1251
	s_waitcnt lgkmcnt(0)
	v_div_scale_f32 v20, s[18:19], v19, v19, 1.0
	v_rcp_f32_e32 v21, v20
	v_div_scale_f32 v22, vcc, 1.0, v19, 1.0
	v_lshlrev_b32_e32 v112, 1, v116
	v_fma_f32 v23, -v20, v21, 1.0
	v_fmac_f32_e32 v21, v23, v21
	v_mul_f32_e32 v23, v22, v21
	v_fma_f32 v24, -v20, v23, v22
	v_fmac_f32_e32 v23, v24, v21
	v_fma_f32 v20, -v20, v23, v22
	v_div_scale_f32 v22, s[18:19], v18, v18, 1.0
	v_rcp_f32_e32 v24, v22
	v_div_fmas_f32 v20, v20, v21, v23
	v_div_fixup_f32 v19, v20, v19, 1.0
	v_fma_f32 v20, -v22, v24, 1.0
	v_fmac_f32_e32 v24, v20, v24
	v_div_scale_f32 v20, vcc, 1.0, v18, 1.0
	v_mul_f32_e32 v21, v20, v24
	v_fma_f32 v23, -v22, v21, v20
	v_fmac_f32_e32 v21, v23, v24
	v_fma_f32 v20, -v22, v21, v20
	v_div_scale_f32 v22, s[18:19], v17, v17, 1.0
	v_rcp_f32_e32 v23, v22
	v_div_fmas_f32 v20, v20, v24, v21
	v_div_fixup_f32 v18, v20, v18, 1.0
	v_fma_f32 v20, -v22, v23, 1.0
	v_fmac_f32_e32 v23, v20, v23
	v_div_scale_f32 v20, vcc, 1.0, v17, 1.0
	v_mul_f32_e32 v21, v20, v23
	v_fma_f32 v24, -v22, v21, v20
	v_fmac_f32_e32 v21, v24, v23
	v_fma_f32 v20, -v22, v21, v20
	v_div_scale_f32 v22, s[18:19], v16, v16, 1.0
	v_rcp_f32_e32 v24, v22
	v_div_fmas_f32 v20, v20, v23, v21
	v_div_fixup_f32 v20, v20, v17, 1.0
	v_fma_f32 v17, -v22, v24, 1.0
	v_fmac_f32_e32 v24, v17, v24
	v_div_scale_f32 v17, vcc, 1.0, v16, 1.0
	v_mul_f32_e32 v21, v17, v24
	v_fma_f32 v23, -v22, v21, v17
	v_fmac_f32_e32 v21, v23, v24
	v_fma_f32 v17, -v22, v21, v17
	v_div_fmas_f32 v17, v17, v24, v21
	v_div_fixup_f32 v21, v17, v16, 1.0
	v_mul_f32_e32 v12, v12, v21
	v_mul_f32_e32 v4, v4, v21
	v_mul_f32_e32 v0, v0, v21
	v_mul_f32_e32 v8, v8, v21
	v_mul_f32_e32 v13, v13, v20
	v_mul_f32_e32 v5, v5, v20
	v_mul_f32_e32 v1, v1, v20
	v_mul_f32_e32 v9, v9, v20
	v_mul_f32_e32 v14, v14, v18
	v_mul_f32_e32 v6, v6, v18
	v_mul_f32_e32 v2, v2, v18
	v_mul_f32_e32 v10, v10, v18
	v_mul_f32_e32 v15, v15, v19
	v_mul_f32_e32 v7, v7, v19
	v_mul_f32_e32 v3, v3, v19
	v_mul_f32_e32 v11, v11, v19
	v_lshl_add_u32 v25, v116, 1, s47
	v_cvt_pk_bf16_f32 v12, v12, v4
	v_cvt_pk_bf16_f32 v0, v0, v8
	v_cvt_pk_bf16_f32 v13, v13, v5
	v_cvt_pk_bf16_f32 v1, v1, v9
	v_cvt_pk_bf16_f32 v14, v14, v6
	v_cvt_pk_bf16_f32 v2, v2, v10
	v_cvt_pk_bf16_f32 v15, v15, v7
	v_cvt_pk_bf16_f32 v3, v3, v11
	ds_write_b16 v25, v12 offset:1024
	ds_write_b16_d16_hi v25, v12 offset:1056
	ds_write_b16 v25, v0 offset:1088
	ds_write_b16_d16_hi v25, v0 offset:1120
	ds_write_b16 v25, v13 offset:1152
	ds_write_b16_d16_hi v25, v13 offset:1184
	ds_write_b16 v25, v1 offset:1216
	ds_write_b16_d16_hi v25, v1 offset:1248
	ds_write_b16 v25, v14 offset:1280
	ds_write_b16_d16_hi v25, v14 offset:1312
	ds_write_b16 v25, v2 offset:1344
	ds_write_b16_d16_hi v25, v2 offset:1376
	ds_write_b16 v25, v15 offset:1408
	ds_write_b16_d16_hi v25, v15 offset:1440
	ds_write_b16 v25, v3 offset:1472
	ds_write_b16_d16_hi v25, v3 offset:1504
	s_mov_b32 exec_lo, -1
	s_mov_b32 exec_hi, 0
	v_lshl_add_u32 v26, v117, 4, s47
	v_lshlrev_b32_e32 v27, 4, v117
	s_add_u32 s18, s16, s14
	s_addc_u32 s19, s17, s15
	ds_read_b128 v[28:31], v26 offset:1024
	s_waitcnt lgkmcnt(0)
	global_store_dwordx4 v27, v[28:31], s[18:19]
	s_branch .LBB0_1251
